# XCD-affine work assignment in the mix phase: block b takes the diff-latent / NA-latent item of (batch,head) pair b&7 first, so each XCD L2 holds one pair's K/V; rest of the queue dynamic
# speedup vs baseline: 1.0147x; 1.0147x over previous
_Z4mega6Paramsii:
	s_load_dwordx2 s[94:95], s[0:1], 0x100
	s_mov_b32 s28, s2
	s_add_u32 s2, s0, 0x110
	s_addc_u32 s3, s1, 0
	v_and_b32_e32 v218, 0x3ff, v0
	v_writelane_b32 v250, s2, 0
	v_cmp_eq_u32_e64 s[30:31], 0, v218
	s_nop 0
	v_writelane_b32 v250, s3, 1
	s_and_saveexec_b64 s[2:3], s[30:31]
	s_cbranch_execz .LBB0_2
	v_mov_b32_e32 v2, 0
	v_mov_b32_e32 v3, v2
	v_mov_b32_e32 v4, s28
	v_mov_b32_e32 v5, v2
	v_mov_b32_e32 v1, 0x12200
	ds_write_b128 v1, v[2:5]

.LBB0_237:
	s_and_b64 vcc, exec, s[0:1]
	s_cbranch_vccz .LBB0_439
	v_readlane_b32 s0, v254, 55
	s_cmp_gt_i32 s0, 0
	s_mov_b64 s[0:1], -1
	s_cbranch_scc0 .LBB0_529
	v_readlane_b32 s0, v254, 55
	s_cmp_gt_i32 s0, 1
	s_mov_b64 s[0:1], -1
	s_cbranch_scc0 .LBB0_441
	s_ashr_i32 s61, s60, 31
	s_lshl_b64 s[0:1], s[60:61], 2
	v_readlane_b32 s2, v250, 36
	v_readlane_b32 s3, v250, 37
	s_add_u32 s0, s2, s0
	s_addc_u32 s1, s3, s1
	v_writelane_b32 v254, s0, 56
	v_readlane_b32 s8, v252, 2
	s_mul_i32 s5, s60, 0x7c00
	v_writelane_b32 v254, s1, 57
	v_readlane_b32 s14, v252, 8
	v_readlane_b32 s0, v254, 53
	s_add_i32 s0, s0, 5
	s_cmp_lt_u32 s0, 13
	s_movk_i32 s0, 0xc20
	s_cselect_b32 s34, s0, 0xa00
	s_lshl_b32 s0, s60, 14
	v_readlane_b32 s1, v254, 54
	v_writelane_b32 v254, s0, 58
	s_lshl_b32 s6, s60, 8
	s_lshl_b32 s0, s60, 7
	s_lshl_b32 s2, s60, 6
	s_ashr_i32 s7, s6, 31
	s_lshl_b32 s39, s60, 2
	s_ashr_i32 s1, s0, 31
	s_ashr_i32 s3, s2, 31
	s_mul_hi_i32 s4, s60, 0x7c00
	v_readlane_b32 s9, v252, 3
	v_readlane_b32 s15, v252, 9
	s_add_u32 s8, s14, s5
	s_addc_u32 s9, s15, s4
	v_writelane_b32 v254, s8, 59
	s_mov_b32 s4, s6
	v_readlane_b32 s18, v252, 12
	v_writelane_b32 v254, s9, 60
	v_writelane_b32 v254, s4, 61
	v_readlane_b32 s19, v252, 13
	v_readlane_b32 s20, v252, 14
	v_writelane_b32 v254, s5, 62
	s_lshl_b64 s[4:5], s[6:7], 2
	s_add_u32 s6, s18, s4
	s_addc_u32 s7, s19, s5
	v_writelane_b32 v254, s6, 63
	v_readlane_b32 s10, v252, 4
	v_readlane_b32 s11, v252, 5
	v_readlane_b32 s12, v252, 6
	v_readlane_b32 s13, v252, 7
	v_readlane_b32 s16, v252, 10
	v_readlane_b32 s17, v252, 11
	v_readlane_b32 s21, v252, 15
	v_readlane_b32 s22, v252, 16
	v_readlane_b32 s23, v252, 17
	v_writelane_b32 v255, s7, 0
	s_add_u32 s6, s20, s4
	s_addc_u32 s7, s21, s5
	v_readlane_b32 s8, v250, 18
	v_writelane_b32 v255, s6, 1
	v_readlane_b32 s20, v250, 30
	v_readlane_b32 s21, v250, 31
	v_writelane_b32 v255, s7, 2
	s_add_u32 s6, s20, s4
	v_readlane_b32 s22, v250, 32
	v_writelane_b32 v255, s6, 3
	s_addc_u32 s6, s21, s5
	v_readlane_b32 s23, v250, 33
	v_writelane_b32 v255, s6, 4
	s_add_u32 s4, s22, s4
	v_readlane_b32 s16, v250, 26
	v_writelane_b32 v255, s4, 5
	s_addc_u32 s4, s23, s5
	s_lshl_b64 s[0:1], s[0:1], 2
	s_waitcnt lgkmcnt(0)
	v_cvt_f32_i32_e32 v0, s60
	v_readlane_b32 s17, v250, 27
	s_add_u32 s0, s16, s0
	v_writelane_b32 v255, s4, 6
	s_addc_u32 s1, s17, s1
	v_writelane_b32 v255, s0, 7
	v_readlane_b32 s18, v250, 28
	v_mul_f32_e32 v0, 0xbe99999a, v0
	v_writelane_b32 v255, s1, 8
	s_lshl_b64 s[0:1], s[2:3], 2
	v_readlane_b32 s19, v250, 29
	s_add_u32 s0, s18, s0
	v_mul_f32_e32 v0, 0x3fb8aa3b, v0
	s_addc_u32 s1, s19, s1
	v_exp_f32_e32 v0, v0
	v_writelane_b32 v255, s0, 9
	v_mov_b32_e32 v2, 0x3f4ccccd
	v_readlane_b32 s9, v250, 19
	v_writelane_b32 v255, s1, 10
	v_writelane_b32 v255, s44, 11
	v_fmamk_f32 v232, v0, 0xbf19999a, v2
	v_sub_f32_e32 v233, 1.0, v232
	v_writelane_b32 v255, s45, 12
	v_writelane_b32 v255, s34, 13
	v_writelane_b32 v255, s39, 14
	v_readlane_b32 s10, v250, 20
	v_readlane_b32 s11, v250, 21
	v_readlane_b32 s12, v250, 22
	v_readlane_b32 s13, v250, 23
	v_readlane_b32 s14, v250, 24
	v_readlane_b32 s15, v250, 25
	v_readlane_b32 s99, v252, 20
	v_mov_b32_e32 v0, 0x12208
	s_cmpk_lg_u32 s99, 0x200
	s_cbranch_scc1 .LBB0_243
	ds_read_b32 v0, v0
	s_waitcnt lgkmcnt(0)
	s_nop 0
	v_readfirstlane_b32 s98, v0
	s_and_b32 s99, s98, 7
	s_lshr_b32 s98, s98, 3
	s_lshl_b32 s99, s99, 5
	s_add_u32 s40, s99, s98
	s_cmpk_lt_u32 s98, 32
	s_cbranch_scc1 .Lmix_first_ok
	s_addk_i32 s40, 0xe0
.Lmix_first_ok:
	v_mov_b32_e32 v0, s40
	s_mov_b64 s[0:1], -1
	s_branch .Lmix_dispatch

.LBB0_247:
	s_or_b64 exec, exec, s[0:1]
	s_waitcnt lgkmcnt(0)
	s_barrier
	ds_read_b32 v0, v220
	s_mov_b64 s[0:1], -1
	s_waitcnt lgkmcnt(0)
	s_barrier
	v_readlane_b32 s99, v252, 20
	s_cmpk_eq_u32 s99, 0x200
	s_cselect_b32 s99, 0x200, 0
	v_add_u32_e32 v0, s99, v0
	v_cmp_le_i32_e32 vcc, s34, v0
	v_readfirstlane_b32 s40, v0
	s_cbranch_vccnz .LBB0_242
.Lmix_dispatch:
	s_cmpk_gt_i32 s40, 0xff
	s_cbranch_scc0 .LBB0_261
	s_cmpk_gt_u32 s40, 0x1ff
	s_cbranch_scc0 .LBB0_262
	s_cmpk_gt_u32 s40, 0x2ff
	s_cbranch_scc0 .LBB0_263
	s_cmpk_gt_u32 s40, 0x3ff
	s_cbranch_scc0 .LBB0_264
	s_cmpk_gt_u32 s40, 0x5ff
	s_cbranch_scc0 .LBB0_265
	s_cmpk_gt_u32 s40, 0x7ff
	s_cbranch_scc0 .LBB0_266
	s_cmpk_gt_u32 s40, 0x9ff
	s_cbranch_scc0 .LBB0_267
	s_cmpk_gt_u32 s40, 0xaff
	s_mov_b64 s[2:3], -1
	s_cbranch_scc0 .LBB0_268
	v_readlane_b32 s12, v252, 2
	v_readlane_b32 s72, v253, 51
	v_readlane_b32 s18, v252, 8
	v_readlane_b32 s20, v252, 10
	v_readlane_b32 s21, v252, 11
	v_readlane_b32 s76, v253, 55
	v_readlane_b32 s77, v253, 56
	s_lshl_b32 s6, s40, 2
	s_mov_b32 s7, -4
	v_readlane_b32 s16, v252, 6
	v_readlane_b32 s17, v252, 7
	s_mov_b64 s[20:21], s[76:77]
	s_movk_i32 s18, 0x104
	v_readlane_b32 s13, v252, 3
	v_readlane_b32 s14, v252, 4
	v_readlane_b32 s15, v252, 5
	v_readlane_b32 s19, v252, 9
	v_readlane_b32 s22, v252, 12
	v_readlane_b32 s23, v252, 13
	v_readlane_b32 s24, v252, 14
	v_readlane_b32 s25, v252, 15
	v_readlane_b32 s26, v252, 16
	v_readlane_b32 s27, v252, 17
	v_readlane_b32 s73, v253, 52
	v_readlane_b32 s74, v253, 53
	v_readlane_b32 s75, v253, 54
	v_readlane_b32 s78, v253, 57
	v_readlane_b32 s79, v253, 58
	v_readlane_b32 s80, v253, 59
	v_readlane_b32 s81, v253, 60
	v_readlane_b32 s82, v253, 61
	v_readlane_b32 s83, v253, 62
	v_readlane_b32 s84, v253, 63
	v_readlane_b32 s85, v254, 0
	v_readlane_b32 s86, v254, 1
	v_readlane_b32 s87, v254, 2
